# scan waves get their own loop latch (barrier, counter, back edge at the end of the body) instead of detouring through the shared latch and header
# speedup vs baseline: 1.0138x; 1.0051x over previous
; __device__ __forceinline__ void phase_scan(const Params& p, LAS unsigned char* lds) {
;     ...
;                     const LAS float* sR = OPS + (n & 1) * SET_F + j0; const LAS float* sW = sR + 2048; const LAS float* sK = sW + 2048; const LAS float* sA = sK + 2048; const LAS float* sB = sA + 2048; const LAS float* sV = OPS + (n & 1) * SET_F + 10240;
;                     LAS float* sY = sYb + (n & 1) * 512;
;                     f32x4 a_ = *(const LAS f32x4*)(sA), w_ = *(const LAS f32x4*)(sW), b_ = *(const LAS f32x4*)(sB);
;                     f32x4 k_ = *(const LAS f32x4*)(sK), r_ = *(const LAS f32x4*)(sR);
;                     f32x4 vq[4];
; #pragma unroll
;                     for (int u = 0; u < 4; ++u) vq[u] = *(const LAS f32x4*)(sV + srow * 32 + 4 * u);
;                     f32x4 rp = r_;
; #pragma unroll
;                     for (int hb = 0; hb < 2; ++hb) {
;                         f32x4 vn[4];
; #pragma unroll
;                         for (int u = 0; u < 4; ++u) vn[u] = *(const LAS f32x4*)(sV + srow * 32 + ((16 * (hb + 1)) & 31) + 4 * u);
; #pragma unroll
;                         for (int u16 = 0; u16 < 16; ++u16) {
;                             const int s = 16 * hb + u16;
;                             const int sn = (s + 1) & 31;
;                             const f32x4 a_n = *(const LAS f32x4*)(sA + sn * 64), w_n = *(const LAS f32x4*)(sW + sn * 64), b_n = *(const LAS f32x4*)(sB + sn * 64);
;                             const f32x4 k_n = *(const LAS f32x4*)(sK + sn * 64), r_n = *(const LAS f32x4*)(sR + sn * 64);
;                             const float v = vq[u16 >> 2][u16 & 3];
;                             const f32x2 vv = {v, v};
;                             f32x2 pp = S01 * (f32x2){a_[0], a_[1]}; pp = S23 * (f32x2){a_[2], a_[3]} + pp;
;                             f32x2 yy = S01 * (f32x2){rp[0], rp[1]}; yy = S23 * (f32x2){rp[2], rp[3]} + yy;
;                             float sa = pp[0] + pp[1], y = yy[0] + yy[1];
;                             sa += dpp_f<0xB1>(sa); y += dpp_f<0xB1>(y);
;                             sa += dpp_f<0x4E>(sa); y += dpp_f<0x4E>(y);
;                             sa += dpp_f<0x141>(sa); y += dpp_f<0x141>(y);
;                             sa += dpp_f<0x140>(sa); y += dpp_f<0x140>(y);
;                             sY[((s - 1) & 31) * 16 + srow] = y;
;                             const f32x2 sv = {sa, sa};
.Lscan_trip:
	s_and_b32 s14, s81, 1
	s_mul_i32 s15, s14, 0xa800
	s_add_i32 s15, s15, 0x8800
	v_add_u32_e32 v124, s15, v178
	v_add_u32_e32 v125, s15, v179
	s_cmp_eq_u32 s81, 0
	s_cselect_b32 s14, 0xc000c000, -1
	s_mov_b32 s15, s14
	v_pk_mul_f32 v[114:115], v[166:167], v[22:23]
	v_pk_mul_f32 v[116:117], v[166:167], v[18:19]
	v_pk_fma_f32 v[114:115], v[164:165], v[24:25], v[114:115]
	v_pk_fma_f32 v[116:117], v[164:165], v[20:21], v[116:117]
	v_add_f32_e32 v122, v114, v115
	v_pk_mul_f32 v[118:119], v[110:111], v[34:35] op_sel:[1,0]
	v_add_f32_e32 v214, v116, v117
	ds_read_b128 v[14:17], v124 offset:16384
	ds_read_b128 v[6:9], v124 offset:8192
	ds_read_b128 v[10:13], v124 offset:32768
	ds_read_b128 v[18:21], v124 offset:0
	ds_read_b128 v[2:5], v124 offset:24576
	ds_read_b128 v[82:85], v125 offset:40960
	v_add_f32_dpp v122, v122, v122 quad_perm:[1,0,3,2] row_mask:0xf bank_mask:0xf bound_ctrl:1
	v_pk_mul_f32 v[120:121], v[110:111], v[36:37] op_sel:[1,0]
	v_add_f32_dpp v204, v204, v204 row_mirror row_mask:0xf bank_mask:0xf bound_ctrl:1
	v_add_f32_dpp v122, v122, v122 quad_perm:[2,3,0,1] row_mask:0xf bank_mask:0xf bound_ctrl:1
	v_pk_fma_f32 v[166:167], v[166:167], v[26:27], v[118:119]
	v_add_f32_dpp v204, v212, v212 row_mirror row_mask:0xf bank_mask:0xc bound_ctrl:1
	v_add_f32_dpp v122, v122, v122 row_half_mirror row_mask:0xf bank_mask:0xf bound_ctrl:1
	v_pk_fma_f32 v[164:165], v[164:165], v[28:29], v[120:121]
	v_add_f32_dpp v205, v205, v205 row_mirror row_mask:0xf bank_mask:0xf bound_ctrl:1
	v_add_f32_dpp v122, v122, v122 row_mirror row_mask:0xf bank_mask:0xf bound_ctrl:1
	v_add_f32_dpp v205, v213, v213 row_mirror row_mask:0xf bank_mask:0xc bound_ctrl:1
	v_add_f32_dpp v206, v206, v206 row_mirror row_mask:0xf bank_mask:0xf bound_ctrl:1
	v_pk_fma_f32 v[166:167], v[30:31], v[122:123], v[166:167] op_sel_hi:[1,0,1]
	v_pk_fma_f32 v[164:165], v[32:33], v[122:123], v[164:165] op_sel_hi:[1,0,1]
	v_add_f32_dpp v206, v214, v214 row_mirror row_mask:0xf bank_mask:0xc bound_ctrl:1
	v_pk_mul_f32 v[114:115], v[166:167], v[42:43]
	v_pk_mul_f32 v[116:117], v[166:167], v[38:39]
	v_pk_fma_f32 v[114:115], v[164:165], v[44:45], v[114:115]
	v_pk_fma_f32 v[116:117], v[164:165], v[40:41], v[116:117]
	v_add_f32_e32 v122, v114, v115
	v_pk_mul_f32 v[118:119], v[112:113], v[54:55] op_sel_hi:[0,1]
	v_add_f32_e32 v215, v116, v117
	ds_read_b128 v[34:37], v124 offset:16640
	ds_read_b128 v[26:29], v124 offset:8448
	ds_read_b128 v[30:33], v124 offset:33024
	ds_read_b128 v[38:41], v124 offset:256
	ds_read_b128 v[22:25], v124 offset:24832
	v_add_f32_dpp v122, v122, v122 quad_perm:[1,0,3,2] row_mask:0xf bank_mask:0xf bound_ctrl:1
	v_pk_mul_f32 v[120:121], v[112:113], v[56:57] op_sel_hi:[0,1]
	v_add_f32_dpp v207, v207, v207 row_mirror row_mask:0xf bank_mask:0xf bound_ctrl:1
	v_add_f32_dpp v122, v122, v122 quad_perm:[2,3,0,1] row_mask:0xf bank_mask:0xf bound_ctrl:1
	v_pk_fma_f32 v[166:167], v[166:167], v[46:47], v[118:119]
	v_add_f32_dpp v207, v215, v215 row_mirror row_mask:0xf bank_mask:0xc bound_ctrl:1
	v_add_f32_dpp v122, v122, v122 row_half_mirror row_mask:0xf bank_mask:0xf bound_ctrl:1
	v_pk_fma_f32 v[164:165], v[164:165], v[48:49], v[120:121]
	s_nop 0
	v_add_f32_dpp v122, v122, v122 row_mirror row_mask:0xf bank_mask:0xf bound_ctrl:1
	s_nop 0
	v_pk_fma_f32 v[166:167], v[50:51], v[122:123], v[166:167] op_sel_hi:[1,0,1]
	v_pk_fma_f32 v[164:165], v[52:53], v[122:123], v[164:165] op_sel_hi:[1,0,1]
	v_pk_mul_f32 v[114:115], v[166:167], v[62:63]
	v_pk_mul_f32 v[116:117], v[166:167], v[58:59]
	v_pk_fma_f32 v[114:115], v[164:165], v[64:65], v[114:115]
	v_pk_fma_f32 v[116:117], v[164:165], v[60:61], v[116:117]
	v_add_f32_e32 v122, v114, v115
	v_pk_mul_f32 v[118:119], v[112:113], v[74:75] op_sel:[1,0]
	v_add_f32_e32 v216, v116, v117
	ds_read_b128 v[54:57], v124 offset:16896
	ds_read_b128 v[46:49], v124 offset:8704
	ds_read_b128 v[50:53], v124 offset:33280
	ds_read_b128 v[58:61], v124 offset:512
	ds_read_b128 v[42:45], v124 offset:25088
	v_add_f32_dpp v122, v122, v122 quad_perm:[1,0,3,2] row_mask:0xf bank_mask:0xf bound_ctrl:1
	v_pk_mul_f32 v[120:121], v[112:113], v[76:77] op_sel:[1,0]
	v_add_f32_dpp v208, v208, v208 row_mirror row_mask:0xf bank_mask:0xf bound_ctrl:1
	v_add_f32_dpp v122, v122, v122 quad_perm:[2,3,0,1] row_mask:0xf bank_mask:0xf bound_ctrl:1
	v_pk_fma_f32 v[166:167], v[166:167], v[66:67], v[118:119]
	v_add_f32_dpp v208, v216, v216 row_mirror row_mask:0xf bank_mask:0xc bound_ctrl:1
	v_add_f32_dpp v122, v122, v122 row_half_mirror row_mask:0xf bank_mask:0xf bound_ctrl:1
	v_pk_fma_f32 v[164:165], v[164:165], v[68:69], v[120:121]
	s_nop 0
	v_add_f32_dpp v122, v122, v122 row_mirror row_mask:0xf bank_mask:0xf bound_ctrl:1
	s_nop 0
	v_pk_fma_f32 v[166:167], v[70:71], v[122:123], v[166:167] op_sel_hi:[1,0,1]
	v_pk_fma_f32 v[164:165], v[72:73], v[122:123], v[164:165] op_sel_hi:[1,0,1]
	s_waitcnt lgkmcnt(11)
	v_pk_mul_f32 v[114:115], v[166:167], v[2:3]
	v_pk_mul_f32 v[116:117], v[166:167], v[78:79]
	v_pk_fma_f32 v[114:115], v[164:165], v[4:5], v[114:115]
	v_pk_fma_f32 v[116:117], v[164:165], v[80:81], v[116:117]
	v_add_f32_e32 v122, v114, v115
	s_waitcnt lgkmcnt(10)
; #define LAS __attribute__((address_space(3)))
; template <int CTRL> __device__ __forceinline__ float dpp_f(float x) { return __int_as_float(__builtin_amdgcn_update_dpp(0, __float_as_int(x), CTRL, 0xf, 0xf, false)); }
; __device__ __forceinline__ void phase_scan(const Params& p, LAS unsigned char* lds) {
;     ...
;                         for (int u16 = 0; u16 < 16; ++u16) {
;                             const int s = 16 * hb + u16;
;                             const int sn = (s + 1) & 31;
;                             const f32x4 a_n = *(const LAS f32x4*)(sA + sn * 64), w_n = *(const LAS f32x4*)(sW + sn * 64), b_n = *(const LAS f32x4*)(sB + sn * 64);
;                             const f32x4 k_n = *(const LAS f32x4*)(sK + sn * 64), r_n = *(const LAS f32x4*)(sR + sn * 64);
;                             const float v = vq[u16 >> 2][u16 & 3];
;                             const f32x2 vv = {v, v};
;                             f32x2 pp = S01 * (f32x2){a_[0], a_[1]}; pp = S23 * (f32x2){a_[2], a_[3]} + pp;
;                             f32x2 yy = S01 * (f32x2){rp[0], rp[1]}; yy = S23 * (f32x2){rp[2], rp[3]} + yy;
;                             float sa = pp[0] + pp[1], y = yy[0] + yy[1];
;                             sa += dpp_f<0xB1>(sa); y += dpp_f<0xB1>(y);
;                             sa += dpp_f<0x4E>(sa); y += dpp_f<0x4E>(y);
;                             sa += dpp_f<0x141>(sa); y += dpp_f<0x141>(y);
;                             sa += dpp_f<0x140>(sa); y += dpp_f<0x140>(y);
;                             sY[((s - 1) & 31) * 16 + srow] = y;
;                             const f32x2 sv = {sa, sa};
;                             S01 = S01 * (f32x2){w_[0], w_[1]} + vv * (f32x2){k_[0], k_[1]};
;                             S23 = S23 * (f32x2){w_[2], w_[3]} + vv * (f32x2){k_[2], k_[3]};
;                             S01 = sv * (f32x2){b_[0], b_[1]} + S01;
;                             S23 = sv * (f32x2){b_[2], b_[3]} + S23;
;                             rp = r_;
;                             a_ = a_n; w_ = w_n; b_ = b_n; k_ = k_n; r_ = r_n;
;                         }
	v_pk_mul_f32 v[118:119], v[82:83], v[14:15] op_sel_hi:[0,1]
	v_add_f32_e32 v217, v116, v117
	ds_read_b128 v[74:77], v124 offset:17152
	ds_read_b128 v[66:69], v124 offset:8960
	ds_read_b128 v[70:73], v124 offset:33536
	ds_read_b128 v[78:81], v124 offset:768
	ds_read_b128 v[62:65], v124 offset:25344
	v_add_f32_dpp v122, v122, v122 quad_perm:[1,0,3,2] row_mask:0xf bank_mask:0xf bound_ctrl:1
	v_pk_mul_f32 v[120:121], v[82:83], v[16:17] op_sel_hi:[0,1]
	v_add_f32_dpp v209, v209, v209 row_mirror row_mask:0xf bank_mask:0xf bound_ctrl:1
	v_add_f32_dpp v122, v122, v122 quad_perm:[2,3,0,1] row_mask:0xf bank_mask:0xf bound_ctrl:1
	v_pk_fma_f32 v[166:167], v[166:167], v[6:7], v[118:119]
	v_add_f32_dpp v209, v217, v217 row_mirror row_mask:0xf bank_mask:0xc bound_ctrl:1
	v_add_f32_dpp v122, v122, v122 row_half_mirror row_mask:0xf bank_mask:0xf bound_ctrl:1
	v_pk_fma_f32 v[164:165], v[164:165], v[8:9], v[120:121]
	s_nop 0
	v_add_f32_dpp v122, v122, v122 row_mirror row_mask:0xf bank_mask:0xf bound_ctrl:1
	s_nop 0
	v_pk_fma_f32 v[166:167], v[10:11], v[122:123], v[166:167] op_sel_hi:[1,0,1]
	v_pk_fma_f32 v[164:165], v[12:13], v[122:123], v[164:165] op_sel_hi:[1,0,1]
	s_waitcnt lgkmcnt(10)
	v_pk_mul_f32 v[114:115], v[166:167], v[22:23]
	v_pk_mul_f32 v[116:117], v[166:167], v[18:19]
	v_pk_fma_f32 v[114:115], v[164:165], v[24:25], v[114:115]
	v_pk_fma_f32 v[116:117], v[164:165], v[20:21], v[116:117]
	v_add_f32_e32 v122, v114, v115
	v_pk_mul_f32 v[118:119], v[82:83], v[34:35] op_sel:[1,0]
	v_add_f32_e32 v218, v116, v117
	ds_read_b128 v[14:17], v124 offset:17408
	ds_read_b128 v[6:9], v124 offset:9216
	ds_read_b128 v[10:13], v124 offset:33792
	ds_read_b128 v[18:21], v124 offset:1024
	ds_read_b128 v[2:5], v124 offset:25600
	ds_read_b128 v[86:89], v125 offset:40976
	v_add_f32_dpp v122, v122, v122 quad_perm:[1,0,3,2] row_mask:0xf bank_mask:0xf bound_ctrl:1
	v_pk_mul_f32 v[120:121], v[82:83], v[36:37] op_sel:[1,0]
	v_add_f32_dpp v210, v210, v210 row_mirror row_mask:0xf bank_mask:0xf bound_ctrl:1
	v_add_f32_dpp v122, v122, v122 quad_perm:[2,3,0,1] row_mask:0xf bank_mask:0xf bound_ctrl:1
	v_pk_fma_f32 v[166:167], v[166:167], v[26:27], v[118:119]
	v_add_f32_dpp v210, v218, v218 row_mirror row_mask:0xf bank_mask:0xc bound_ctrl:1
	v_add_f32_dpp v122, v122, v122 row_half_mirror row_mask:0xf bank_mask:0xf bound_ctrl:1
	v_pk_fma_f32 v[164:165], v[164:165], v[28:29], v[120:121]
	s_nop 0
	v_add_f32_dpp v122, v122, v122 row_mirror row_mask:0xf bank_mask:0xf bound_ctrl:1
	s_nop 0
	v_pk_fma_f32 v[166:167], v[30:31], v[122:123], v[166:167] op_sel_hi:[1,0,1]
	v_pk_fma_f32 v[164:165], v[32:33], v[122:123], v[164:165] op_sel_hi:[1,0,1]
	s_waitcnt lgkmcnt(11)
	v_pk_mul_f32 v[114:115], v[166:167], v[42:43]
	v_pk_mul_f32 v[116:117], v[166:167], v[38:39]
	v_pk_fma_f32 v[114:115], v[164:165], v[44:45], v[114:115]
	v_pk_fma_f32 v[116:117], v[164:165], v[40:41], v[116:117]
	v_add_f32_e32 v122, v114, v115
	v_pk_mul_f32 v[118:119], v[84:85], v[54:55] op_sel_hi:[0,1]
	v_add_f32_e32 v219, v116, v117
	ds_read_b128 v[34:37], v124 offset:17664
	ds_read_b128 v[26:29], v124 offset:9472
	ds_read_b128 v[30:33], v124 offset:34048
	ds_read_b128 v[38:41], v124 offset:1280
	ds_read_b128 v[22:25], v124 offset:25856
	v_add_f32_dpp v122, v122, v122 quad_perm:[1,0,3,2] row_mask:0xf bank_mask:0xf bound_ctrl:1
	v_pk_mul_f32 v[120:121], v[84:85], v[56:57] op_sel_hi:[0,1]
	v_add_f32_dpp v211, v211, v211 row_mirror row_mask:0xf bank_mask:0xf bound_ctrl:1
	v_add_f32_dpp v122, v122, v122 quad_perm:[2,3,0,1] row_mask:0xf bank_mask:0xf bound_ctrl:1
	v_pk_fma_f32 v[166:167], v[166:167], v[46:47], v[118:119]
	v_add_f32_dpp v211, v219, v219 row_mirror row_mask:0xf bank_mask:0xc bound_ctrl:1
	v_add_f32_dpp v122, v122, v122 row_half_mirror row_mask:0xf bank_mask:0xf bound_ctrl:1
	v_pk_fma_f32 v[164:165], v[164:165], v[48:49], v[120:121]
	v_add_f32_dpp v204, v204, v204 row_half_mirror row_mask:0xf bank_mask:0xf bound_ctrl:1
	v_add_f32_dpp v122, v122, v122 row_mirror row_mask:0xf bank_mask:0xf bound_ctrl:1
	v_add_f32_dpp v205, v205, v205 row_half_mirror row_mask:0xf bank_mask:0xf bound_ctrl:1
	v_add_f32_dpp v206, v206, v206 row_half_mirror row_mask:0xf bank_mask:0xf bound_ctrl:1
	v_pk_fma_f32 v[166:167], v[50:51], v[122:123], v[166:167] op_sel_hi:[1,0,1]
	v_pk_fma_f32 v[164:165], v[52:53], v[122:123], v[164:165] op_sel_hi:[1,0,1]
	v_add_f32_dpp v207, v207, v207 row_half_mirror row_mask:0xf bank_mask:0xf bound_ctrl:1
	v_add_f32_dpp v204, v208, v208 row_half_mirror row_mask:0xf bank_mask:0xa bound_ctrl:1
	s_waitcnt lgkmcnt(11)
	v_pk_mul_f32 v[114:115], v[166:167], v[62:63]
	v_pk_mul_f32 v[116:117], v[166:167], v[58:59]
	v_pk_fma_f32 v[114:115], v[164:165], v[64:65], v[114:115]
	v_pk_fma_f32 v[116:117], v[164:165], v[60:61], v[116:117]
	v_add_f32_e32 v122, v114, v115
	v_pk_mul_f32 v[118:119], v[84:85], v[74:75] op_sel:[1,0]
	v_add_f32_e32 v220, v116, v117
	ds_read_b128 v[54:57], v124 offset:17920
	ds_read_b128 v[46:49], v124 offset:9728
	ds_read_b128 v[50:53], v124 offset:34304
	ds_read_b128 v[58:61], v124 offset:1536
	ds_read_b128 v[42:45], v124 offset:26112
	v_add_f32_dpp v122, v122, v122 quad_perm:[1,0,3,2] row_mask:0xf bank_mask:0xf bound_ctrl:1
	v_pk_mul_f32 v[120:121], v[84:85], v[76:77] op_sel:[1,0]
	v_add_f32_dpp v205, v209, v209 row_half_mirror row_mask:0xf bank_mask:0xa bound_ctrl:1
	v_add_f32_dpp v122, v122, v122 quad_perm:[2,3,0,1] row_mask:0xf bank_mask:0xf bound_ctrl:1
	v_pk_fma_f32 v[166:167], v[166:167], v[66:67], v[118:119]
	v_add_f32_dpp v206, v210, v210 row_half_mirror row_mask:0xf bank_mask:0xa bound_ctrl:1
	v_add_f32_dpp v122, v122, v122 row_half_mirror row_mask:0xf bank_mask:0xf bound_ctrl:1
	v_pk_fma_f32 v[164:165], v[164:165], v[68:69], v[120:121]
	v_add_f32_dpp v207, v211, v211 row_half_mirror row_mask:0xf bank_mask:0xa bound_ctrl:1
	v_add_f32_dpp v122, v122, v122 row_mirror row_mask:0xf bank_mask:0xf bound_ctrl:1
	v_add_f32_dpp v204, v204, v204 quad_perm:[1,0,3,2] row_mask:0xf bank_mask:0xf bound_ctrl:1
	v_add_f32_dpp v205, v205, v205 quad_perm:[1,0,3,2] row_mask:0xf bank_mask:0xf bound_ctrl:1
	v_pk_fma_f32 v[166:167], v[70:71], v[122:123], v[166:167] op_sel_hi:[1,0,1]
	v_pk_fma_f32 v[164:165], v[72:73], v[122:123], v[164:165] op_sel_hi:[1,0,1]
	v_add_f32_dpp v206, v206, v206 quad_perm:[1,0,3,2] row_mask:0xf bank_mask:0xf bound_ctrl:1
	v_add_f32_dpp v207, v207, v207 quad_perm:[1,0,3,2] row_mask:0xf bank_mask:0xf bound_ctrl:1
	s_waitcnt lgkmcnt(11)
; #define LAS __attribute__((address_space(3)))
; template <int CTRL> __device__ __forceinline__ float dpp_f(float x) { return __int_as_float(__builtin_amdgcn_update_dpp(0, __float_as_int(x), CTRL, 0xf, 0xf, false)); }
; __device__ __forceinline__ void phase_scan(const Params& p, LAS unsigned char* lds) {
;     ...
;                         for (int u16 = 0; u16 < 16; ++u16) {
;                             const int s = 16 * hb + u16;
;                             const int sn = (s + 1) & 31;
;                             const f32x4 a_n = *(const LAS f32x4*)(sA + sn * 64), w_n = *(const LAS f32x4*)(sW + sn * 64), b_n = *(const LAS f32x4*)(sB + sn * 64);
;                             const f32x4 k_n = *(const LAS f32x4*)(sK + sn * 64), r_n = *(const LAS f32x4*)(sR + sn * 64);
;                             const float v = vq[u16 >> 2][u16 & 3];
;                             const f32x2 vv = {v, v};
;                             f32x2 pp = S01 * (f32x2){a_[0], a_[1]}; pp = S23 * (f32x2){a_[2], a_[3]} + pp;
;                             f32x2 yy = S01 * (f32x2){rp[0], rp[1]}; yy = S23 * (f32x2){rp[2], rp[3]} + yy;
;                             float sa = pp[0] + pp[1], y = yy[0] + yy[1];
;                             sa += dpp_f<0xB1>(sa); y += dpp_f<0xB1>(y);
;                             sa += dpp_f<0x4E>(sa); y += dpp_f<0x4E>(y);
;                             sa += dpp_f<0x141>(sa); y += dpp_f<0x141>(y);
;                             sa += dpp_f<0x140>(sa); y += dpp_f<0x140>(y);
;                             sY[((s - 1) & 31) * 16 + srow] = y;
;                             const f32x2 sv = {sa, sa};
;                             S01 = S01 * (f32x2){w_[0], w_[1]} + vv * (f32x2){k_[0], k_[1]};
;                             S23 = S23 * (f32x2){w_[2], w_[3]} + vv * (f32x2){k_[2], k_[3]};
;                             S01 = sv * (f32x2){b_[0], b_[1]} + S01;
;                             S23 = sv * (f32x2){b_[2], b_[3]} + S23;
;                             rp = r_;
;                             a_ = a_n; w_ = w_n; b_ = b_n; k_ = k_n; r_ = r_n;
;                         }
	v_pk_mul_f32 v[114:115], v[166:167], v[2:3]
	v_pk_mul_f32 v[116:117], v[166:167], v[78:79]
	v_pk_fma_f32 v[114:115], v[164:165], v[4:5], v[114:115]
	v_pk_fma_f32 v[116:117], v[164:165], v[80:81], v[116:117]
	v_add_f32_e32 v122, v114, v115
	s_waitcnt lgkmcnt(10)
	v_pk_mul_f32 v[118:119], v[86:87], v[14:15] op_sel_hi:[0,1]
	v_add_f32_e32 v221, v116, v117
	ds_read_b128 v[74:77], v124 offset:18176
	ds_read_b128 v[66:69], v124 offset:9984
	ds_read_b128 v[70:73], v124 offset:34560
	ds_read_b128 v[78:81], v124 offset:1792
	ds_read_b128 v[62:65], v124 offset:26368
	v_add_f32_dpp v122, v122, v122 quad_perm:[1,0,3,2] row_mask:0xf bank_mask:0xf bound_ctrl:1
	v_pk_mul_f32 v[120:121], v[86:87], v[16:17] op_sel_hi:[0,1]
	v_add_f32_dpp v204, v204, v204 quad_perm:[2,3,0,1] row_mask:0xf bank_mask:0xf bound_ctrl:1
	v_add_f32_dpp v122, v122, v122 quad_perm:[2,3,0,1] row_mask:0xf bank_mask:0xf bound_ctrl:1
	v_pk_fma_f32 v[166:167], v[166:167], v[6:7], v[118:119]
	v_add_f32_dpp v205, v205, v205 quad_perm:[2,3,0,1] row_mask:0xf bank_mask:0xf bound_ctrl:1
	v_add_f32_dpp v122, v122, v122 row_half_mirror row_mask:0xf bank_mask:0xf bound_ctrl:1
	v_pk_fma_f32 v[164:165], v[164:165], v[8:9], v[120:121]
	v_add_f32_dpp v206, v206, v206 quad_perm:[2,3,0,1] row_mask:0xf bank_mask:0xf bound_ctrl:1
	v_add_f32_dpp v122, v122, v122 row_mirror row_mask:0xf bank_mask:0xf bound_ctrl:1
	v_add_f32_dpp v207, v207, v207 quad_perm:[2,3,0,1] row_mask:0xf bank_mask:0xf bound_ctrl:1
	v_cndmask_b32_e64 v202, v204, v205, s[34:35]
	v_pk_fma_f32 v[166:167], v[10:11], v[122:123], v[166:167] op_sel_hi:[1,0,1]
	v_pk_fma_f32 v[164:165], v[12:13], v[122:123], v[164:165] op_sel_hi:[1,0,1]
	v_cndmask_b32_e64 v202, v202, v206, s[56:57]
	v_cndmask_b32_e64 v202, v202, v207, s[98:99]
	s_waitcnt lgkmcnt(10)
	v_pk_mul_f32 v[114:115], v[166:167], v[22:23]
	v_pk_mul_f32 v[116:117], v[166:167], v[18:19]
	v_pk_fma_f32 v[114:115], v[164:165], v[24:25], v[114:115]
	v_pk_fma_f32 v[116:117], v[164:165], v[20:21], v[116:117]
	v_add_f32_e32 v122, v114, v115
	v_pk_mul_f32 v[118:119], v[86:87], v[34:35] op_sel:[1,0]
	v_add_f32_e32 v222, v116, v117
	ds_read_b128 v[14:17], v124 offset:18432
	ds_read_b128 v[6:9], v124 offset:10240
	ds_read_b128 v[10:13], v124 offset:34816
	ds_read_b128 v[18:21], v124 offset:2048
	ds_read_b128 v[2:5], v124 offset:26624
	ds_read_b128 v[90:93], v125 offset:40992
	v_add_f32_dpp v122, v122, v122 quad_perm:[1,0,3,2] row_mask:0xf bank_mask:0xf bound_ctrl:1
	v_pk_mul_f32 v[120:121], v[86:87], v[36:37] op_sel:[1,0]
	v_cvt_f16_f32_e32 v203, v202
	v_add_f32_dpp v122, v122, v122 quad_perm:[2,3,0,1] row_mask:0xf bank_mask:0xf bound_ctrl:1
	v_pk_fma_f32 v[166:167], v[166:167], v[26:27], v[118:119]
	s_mov_b64 exec, s[14:15]
	global_store_short v[128:129], v203, off
	s_mov_b64 exec, -1
	v_add_f32_dpp v122, v122, v122 row_half_mirror row_mask:0xf bank_mask:0xf bound_ctrl:1
	v_pk_fma_f32 v[164:165], v[164:165], v[28:29], v[120:121]
	v_lshl_add_u64 v[128:129], v[128:129], 0, s[100:101]
	v_add_f32_dpp v122, v122, v122 row_mirror row_mask:0xf bank_mask:0xf bound_ctrl:1
	s_nop 0
	v_pk_fma_f32 v[166:167], v[30:31], v[122:123], v[166:167] op_sel_hi:[1,0,1]
	v_pk_fma_f32 v[164:165], v[32:33], v[122:123], v[164:165] op_sel_hi:[1,0,1]
	s_waitcnt lgkmcnt(11)
	v_pk_mul_f32 v[114:115], v[166:167], v[42:43]
	v_pk_mul_f32 v[116:117], v[166:167], v[38:39]
	v_pk_fma_f32 v[114:115], v[164:165], v[44:45], v[114:115]
	v_pk_fma_f32 v[116:117], v[164:165], v[40:41], v[116:117]
	v_add_f32_e32 v122, v114, v115
	v_pk_mul_f32 v[118:119], v[88:89], v[54:55] op_sel_hi:[0,1]
	v_add_f32_e32 v223, v116, v117
	ds_read_b128 v[34:37], v124 offset:18688
	ds_read_b128 v[26:29], v124 offset:10496
	ds_read_b128 v[30:33], v124 offset:35072
	ds_read_b128 v[38:41], v124 offset:2304
	ds_read_b128 v[22:25], v124 offset:26880
	v_add_f32_dpp v122, v122, v122 quad_perm:[1,0,3,2] row_mask:0xf bank_mask:0xf bound_ctrl:1
	v_pk_mul_f32 v[120:121], v[88:89], v[56:57] op_sel_hi:[0,1]
	s_nop 0
	v_add_f32_dpp v122, v122, v122 quad_perm:[2,3,0,1] row_mask:0xf bank_mask:0xf bound_ctrl:1
	v_pk_fma_f32 v[166:167], v[166:167], v[46:47], v[118:119]
	s_nop 0
	v_add_f32_dpp v122, v122, v122 row_half_mirror row_mask:0xf bank_mask:0xf bound_ctrl:1
	v_pk_fma_f32 v[164:165], v[164:165], v[48:49], v[120:121]
	s_nop 0
	v_add_f32_dpp v122, v122, v122 row_mirror row_mask:0xf bank_mask:0xf bound_ctrl:1
	s_nop 0
	v_pk_fma_f32 v[166:167], v[50:51], v[122:123], v[166:167] op_sel_hi:[1,0,1]
	v_pk_fma_f32 v[164:165], v[52:53], v[122:123], v[164:165] op_sel_hi:[1,0,1]
	s_waitcnt lgkmcnt(11)
	v_pk_mul_f32 v[114:115], v[166:167], v[62:63]
	v_pk_mul_f32 v[116:117], v[166:167], v[58:59]
	v_pk_fma_f32 v[114:115], v[164:165], v[64:65], v[114:115]
	v_pk_fma_f32 v[116:117], v[164:165], v[60:61], v[116:117]
	v_add_f32_e32 v122, v114, v115
	v_pk_mul_f32 v[118:119], v[88:89], v[74:75] op_sel:[1,0]
	v_add_f32_e32 v224, v116, v117
	ds_read_b128 v[54:57], v124 offset:18944
	ds_read_b128 v[46:49], v124 offset:10752
	ds_read_b128 v[50:53], v124 offset:35328
	ds_read_b128 v[58:61], v124 offset:2560
	ds_read_b128 v[42:45], v124 offset:27136
	v_add_f32_dpp v122, v122, v122 quad_perm:[1,0,3,2] row_mask:0xf bank_mask:0xf bound_ctrl:1
	v_pk_mul_f32 v[120:121], v[88:89], v[76:77] op_sel:[1,0]
	s_nop 0
	v_add_f32_dpp v122, v122, v122 quad_perm:[2,3,0,1] row_mask:0xf bank_mask:0xf bound_ctrl:1
	v_pk_fma_f32 v[166:167], v[166:167], v[66:67], v[118:119]
	s_nop 0
	v_add_f32_dpp v122, v122, v122 row_half_mirror row_mask:0xf bank_mask:0xf bound_ctrl:1
	v_pk_fma_f32 v[164:165], v[164:165], v[68:69], v[120:121]
	s_nop 0
	v_add_f32_dpp v122, v122, v122 row_mirror row_mask:0xf bank_mask:0xf bound_ctrl:1
	s_nop 0
	v_pk_fma_f32 v[166:167], v[70:71], v[122:123], v[166:167] op_sel_hi:[1,0,1]
	v_pk_fma_f32 v[164:165], v[72:73], v[122:123], v[164:165] op_sel_hi:[1,0,1]
	s_waitcnt lgkmcnt(11)
; #define LAS __attribute__((address_space(3)))
; template <int CTRL> __device__ __forceinline__ float dpp_f(float x) { return __int_as_float(__builtin_amdgcn_update_dpp(0, __float_as_int(x), CTRL, 0xf, 0xf, false)); }
; __device__ __forceinline__ void phase_scan(const Params& p, LAS unsigned char* lds) {
;     ...
;                         for (int u16 = 0; u16 < 16; ++u16) {
;                             const int s = 16 * hb + u16;
;                             const int sn = (s + 1) & 31;
;                             const f32x4 a_n = *(const LAS f32x4*)(sA + sn * 64), w_n = *(const LAS f32x4*)(sW + sn * 64), b_n = *(const LAS f32x4*)(sB + sn * 64);
;                             const f32x4 k_n = *(const LAS f32x4*)(sK + sn * 64), r_n = *(const LAS f32x4*)(sR + sn * 64);
;                             const float v = vq[u16 >> 2][u16 & 3];
;                             const f32x2 vv = {v, v};
;                             f32x2 pp = S01 * (f32x2){a_[0], a_[1]}; pp = S23 * (f32x2){a_[2], a_[3]} + pp;
;                             f32x2 yy = S01 * (f32x2){rp[0], rp[1]}; yy = S23 * (f32x2){rp[2], rp[3]} + yy;
;                             float sa = pp[0] + pp[1], y = yy[0] + yy[1];
;                             sa += dpp_f<0xB1>(sa); y += dpp_f<0xB1>(y);
;                             sa += dpp_f<0x4E>(sa); y += dpp_f<0x4E>(y);
;                             sa += dpp_f<0x141>(sa); y += dpp_f<0x141>(y);
;                             sa += dpp_f<0x140>(sa); y += dpp_f<0x140>(y);
;                             sY[((s - 1) & 31) * 16 + srow] = y;
;                             const f32x2 sv = {sa, sa};
;                             S01 = S01 * (f32x2){w_[0], w_[1]} + vv * (f32x2){k_[0], k_[1]};
;                             S23 = S23 * (f32x2){w_[2], w_[3]} + vv * (f32x2){k_[2], k_[3]};
;                             S01 = sv * (f32x2){b_[0], b_[1]} + S01;
;                             S23 = sv * (f32x2){b_[2], b_[3]} + S23;
;                             rp = r_;
;                             a_ = a_n; w_ = w_n; b_ = b_n; k_ = k_n; r_ = r_n;
;                         }
	v_pk_mul_f32 v[114:115], v[166:167], v[2:3]
	v_pk_mul_f32 v[116:117], v[166:167], v[78:79]
	v_pk_fma_f32 v[114:115], v[164:165], v[4:5], v[114:115]
	v_pk_fma_f32 v[116:117], v[164:165], v[80:81], v[116:117]
	v_add_f32_e32 v122, v114, v115
	s_waitcnt lgkmcnt(10)
	v_pk_mul_f32 v[118:119], v[90:91], v[14:15] op_sel_hi:[0,1]
	v_add_f32_e32 v225, v116, v117
	ds_read_b128 v[74:77], v124 offset:19200
	ds_read_b128 v[66:69], v124 offset:11008
	ds_read_b128 v[70:73], v124 offset:35584
	ds_read_b128 v[78:81], v124 offset:2816
	ds_read_b128 v[62:65], v124 offset:27392
	v_add_f32_dpp v122, v122, v122 quad_perm:[1,0,3,2] row_mask:0xf bank_mask:0xf bound_ctrl:1
	v_pk_mul_f32 v[120:121], v[90:91], v[16:17] op_sel_hi:[0,1]
	s_nop 0
	v_add_f32_dpp v122, v122, v122 quad_perm:[2,3,0,1] row_mask:0xf bank_mask:0xf bound_ctrl:1
	v_pk_fma_f32 v[166:167], v[166:167], v[6:7], v[118:119]
	s_nop 0
	v_add_f32_dpp v122, v122, v122 row_half_mirror row_mask:0xf bank_mask:0xf bound_ctrl:1
	v_pk_fma_f32 v[164:165], v[164:165], v[8:9], v[120:121]
	s_nop 0
	v_add_f32_dpp v122, v122, v122 row_mirror row_mask:0xf bank_mask:0xf bound_ctrl:1
	s_nop 0
	v_pk_fma_f32 v[166:167], v[10:11], v[122:123], v[166:167] op_sel_hi:[1,0,1]
	v_pk_fma_f32 v[164:165], v[12:13], v[122:123], v[164:165] op_sel_hi:[1,0,1]
	s_waitcnt lgkmcnt(10)
	v_pk_mul_f32 v[114:115], v[166:167], v[22:23]
	v_pk_mul_f32 v[116:117], v[166:167], v[18:19]
	v_pk_fma_f32 v[114:115], v[164:165], v[24:25], v[114:115]
	v_pk_fma_f32 v[116:117], v[164:165], v[20:21], v[116:117]
	v_add_f32_e32 v122, v114, v115
	v_pk_mul_f32 v[118:119], v[90:91], v[34:35] op_sel:[1,0]
	v_add_f32_e32 v226, v116, v117
	ds_read_b128 v[14:17], v124 offset:19456
	ds_read_b128 v[6:9], v124 offset:11264
	ds_read_b128 v[10:13], v124 offset:35840
	ds_read_b128 v[18:21], v124 offset:3072
	ds_read_b128 v[2:5], v124 offset:27648
	ds_read_b128 v[94:97], v125 offset:41008
	v_add_f32_dpp v122, v122, v122 quad_perm:[1,0,3,2] row_mask:0xf bank_mask:0xf bound_ctrl:1
	v_pk_mul_f32 v[120:121], v[90:91], v[36:37] op_sel:[1,0]
	s_nop 0
	v_add_f32_dpp v122, v122, v122 quad_perm:[2,3,0,1] row_mask:0xf bank_mask:0xf bound_ctrl:1
	v_pk_fma_f32 v[166:167], v[166:167], v[26:27], v[118:119]
	s_nop 0
	v_add_f32_dpp v122, v122, v122 row_half_mirror row_mask:0xf bank_mask:0xf bound_ctrl:1
	v_pk_fma_f32 v[164:165], v[164:165], v[28:29], v[120:121]
	s_nop 0
	v_add_f32_dpp v122, v122, v122 row_mirror row_mask:0xf bank_mask:0xf bound_ctrl:1
	s_nop 0
	v_pk_fma_f32 v[166:167], v[30:31], v[122:123], v[166:167] op_sel_hi:[1,0,1]
	v_pk_fma_f32 v[164:165], v[32:33], v[122:123], v[164:165] op_sel_hi:[1,0,1]
	s_waitcnt lgkmcnt(11)
	v_pk_mul_f32 v[114:115], v[166:167], v[42:43]
	v_pk_mul_f32 v[116:117], v[166:167], v[38:39]
	v_pk_fma_f32 v[114:115], v[164:165], v[44:45], v[114:115]
	v_pk_fma_f32 v[116:117], v[164:165], v[40:41], v[116:117]
	v_add_f32_e32 v122, v114, v115
	v_pk_mul_f32 v[118:119], v[92:93], v[54:55] op_sel_hi:[0,1]
	v_add_f32_e32 v227, v116, v117
	ds_read_b128 v[34:37], v124 offset:19712
	ds_read_b128 v[26:29], v124 offset:11520
	ds_read_b128 v[30:33], v124 offset:36096
	ds_read_b128 v[38:41], v124 offset:3328
	ds_read_b128 v[22:25], v124 offset:27904
	v_add_f32_dpp v122, v122, v122 quad_perm:[1,0,3,2] row_mask:0xf bank_mask:0xf bound_ctrl:1
	v_pk_mul_f32 v[120:121], v[92:93], v[56:57] op_sel_hi:[0,1]
	s_nop 0
	v_add_f32_dpp v122, v122, v122 quad_perm:[2,3,0,1] row_mask:0xf bank_mask:0xf bound_ctrl:1
	v_pk_fma_f32 v[166:167], v[166:167], v[46:47], v[118:119]
	s_nop 0
	v_add_f32_dpp v122, v122, v122 row_half_mirror row_mask:0xf bank_mask:0xf bound_ctrl:1
	v_pk_fma_f32 v[164:165], v[164:165], v[48:49], v[120:121]
	s_nop 0
	v_add_f32_dpp v122, v122, v122 row_mirror row_mask:0xf bank_mask:0xf bound_ctrl:1
	s_nop 0
	v_pk_fma_f32 v[166:167], v[50:51], v[122:123], v[166:167] op_sel_hi:[1,0,1]
	v_pk_fma_f32 v[164:165], v[52:53], v[122:123], v[164:165] op_sel_hi:[1,0,1]
	s_waitcnt lgkmcnt(11)
	v_pk_mul_f32 v[114:115], v[166:167], v[62:63]
	v_pk_mul_f32 v[116:117], v[166:167], v[58:59]
	v_pk_fma_f32 v[114:115], v[164:165], v[64:65], v[114:115]
	v_pk_fma_f32 v[116:117], v[164:165], v[60:61], v[116:117]
	v_add_f32_e32 v122, v114, v115
	v_pk_mul_f32 v[118:119], v[92:93], v[74:75] op_sel:[1,0]
	v_add_f32_e32 v228, v116, v117
	ds_read_b128 v[54:57], v124 offset:19968
	ds_read_b128 v[46:49], v124 offset:11776
	ds_read_b128 v[50:53], v124 offset:36352
	ds_read_b128 v[58:61], v124 offset:3584
	ds_read_b128 v[42:45], v124 offset:28160
	v_add_f32_dpp v122, v122, v122 quad_perm:[1,0,3,2] row_mask:0xf bank_mask:0xf bound_ctrl:1
	v_pk_mul_f32 v[120:121], v[92:93], v[76:77] op_sel:[1,0]
	v_add_f32_dpp v220, v220, v220 row_mirror row_mask:0xf bank_mask:0xf bound_ctrl:1
	v_add_f32_dpp v122, v122, v122 quad_perm:[2,3,0,1] row_mask:0xf bank_mask:0xf bound_ctrl:1
	v_pk_fma_f32 v[166:167], v[166:167], v[66:67], v[118:119]
	v_add_f32_dpp v220, v228, v228 row_mirror row_mask:0xf bank_mask:0xc bound_ctrl:1
	v_add_f32_dpp v122, v122, v122 row_half_mirror row_mask:0xf bank_mask:0xf bound_ctrl:1
	v_pk_fma_f32 v[164:165], v[164:165], v[68:69], v[120:121]
	s_nop 0
	v_add_f32_dpp v122, v122, v122 row_mirror row_mask:0xf bank_mask:0xf bound_ctrl:1
	s_nop 0
	v_pk_fma_f32 v[166:167], v[70:71], v[122:123], v[166:167] op_sel_hi:[1,0,1]
	v_pk_fma_f32 v[164:165], v[72:73], v[122:123], v[164:165] op_sel_hi:[1,0,1]
	s_waitcnt lgkmcnt(11)
	v_pk_mul_f32 v[114:115], v[166:167], v[2:3]
	v_pk_mul_f32 v[116:117], v[166:167], v[78:79]
	v_pk_fma_f32 v[114:115], v[164:165], v[4:5], v[114:115]
	v_pk_fma_f32 v[116:117], v[164:165], v[80:81], v[116:117]
	v_add_f32_e32 v122, v114, v115
	s_waitcnt lgkmcnt(10)
; #define LAS __attribute__((address_space(3)))
; template <int CTRL> __device__ __forceinline__ float dpp_f(float x) { return __int_as_float(__builtin_amdgcn_update_dpp(0, __float_as_int(x), CTRL, 0xf, 0xf, false)); }
; __device__ __forceinline__ void phase_scan(const Params& p, LAS unsigned char* lds) {
;     ...
;                         for (int u16 = 0; u16 < 16; ++u16) {
;                             const int s = 16 * hb + u16;
;                             const int sn = (s + 1) & 31;
;                             const f32x4 a_n = *(const LAS f32x4*)(sA + sn * 64), w_n = *(const LAS f32x4*)(sW + sn * 64), b_n = *(const LAS f32x4*)(sB + sn * 64);
;                             const f32x4 k_n = *(const LAS f32x4*)(sK + sn * 64), r_n = *(const LAS f32x4*)(sR + sn * 64);
;                             const float v = vq[u16 >> 2][u16 & 3];
;                             const f32x2 vv = {v, v};
;                             f32x2 pp = S01 * (f32x2){a_[0], a_[1]}; pp = S23 * (f32x2){a_[2], a_[3]} + pp;
;                             f32x2 yy = S01 * (f32x2){rp[0], rp[1]}; yy = S23 * (f32x2){rp[2], rp[3]} + yy;
;                             float sa = pp[0] + pp[1], y = yy[0] + yy[1];
;                             sa += dpp_f<0xB1>(sa); y += dpp_f<0xB1>(y);
;                             sa += dpp_f<0x4E>(sa); y += dpp_f<0x4E>(y);
;                             sa += dpp_f<0x141>(sa); y += dpp_f<0x141>(y);
;                             sa += dpp_f<0x140>(sa); y += dpp_f<0x140>(y);
;                             sY[((s - 1) & 31) * 16 + srow] = y;
;                             const f32x2 sv = {sa, sa};
;                             S01 = S01 * (f32x2){w_[0], w_[1]} + vv * (f32x2){k_[0], k_[1]};
;                             S23 = S23 * (f32x2){w_[2], w_[3]} + vv * (f32x2){k_[2], k_[3]};
;                             S01 = sv * (f32x2){b_[0], b_[1]} + S01;
;                             S23 = sv * (f32x2){b_[2], b_[3]} + S23;
;                             rp = r_;
;                             a_ = a_n; w_ = w_n; b_ = b_n; k_ = k_n; r_ = r_n;
;                         }
	v_pk_mul_f32 v[118:119], v[94:95], v[14:15] op_sel_hi:[0,1]
	v_add_f32_e32 v229, v116, v117
	ds_read_b128 v[74:77], v124 offset:20224
	ds_read_b128 v[66:69], v124 offset:12032
	ds_read_b128 v[70:73], v124 offset:36608
	ds_read_b128 v[78:81], v124 offset:3840
	ds_read_b128 v[62:65], v124 offset:28416
	v_add_f32_dpp v122, v122, v122 quad_perm:[1,0,3,2] row_mask:0xf bank_mask:0xf bound_ctrl:1
	v_pk_mul_f32 v[120:121], v[94:95], v[16:17] op_sel_hi:[0,1]
	v_add_f32_dpp v221, v221, v221 row_mirror row_mask:0xf bank_mask:0xf bound_ctrl:1
	v_add_f32_dpp v122, v122, v122 quad_perm:[2,3,0,1] row_mask:0xf bank_mask:0xf bound_ctrl:1
	v_pk_fma_f32 v[166:167], v[166:167], v[6:7], v[118:119]
	v_add_f32_dpp v221, v229, v229 row_mirror row_mask:0xf bank_mask:0xc bound_ctrl:1
	v_add_f32_dpp v122, v122, v122 row_half_mirror row_mask:0xf bank_mask:0xf bound_ctrl:1
	v_pk_fma_f32 v[164:165], v[164:165], v[8:9], v[120:121]
	s_nop 0
	v_add_f32_dpp v122, v122, v122 row_mirror row_mask:0xf bank_mask:0xf bound_ctrl:1
	s_nop 0
	v_pk_fma_f32 v[166:167], v[10:11], v[122:123], v[166:167] op_sel_hi:[1,0,1]
	v_pk_fma_f32 v[164:165], v[12:13], v[122:123], v[164:165] op_sel_hi:[1,0,1]
	s_waitcnt lgkmcnt(10)
	v_pk_mul_f32 v[114:115], v[166:167], v[22:23]
	v_pk_mul_f32 v[116:117], v[166:167], v[18:19]
	v_pk_fma_f32 v[114:115], v[164:165], v[24:25], v[114:115]
	v_pk_fma_f32 v[116:117], v[164:165], v[20:21], v[116:117]
	v_add_f32_e32 v122, v114, v115
	v_pk_mul_f32 v[118:119], v[94:95], v[34:35] op_sel:[1,0]
	v_add_f32_e32 v230, v116, v117
	ds_read_b128 v[14:17], v124 offset:20480
	ds_read_b128 v[6:9], v124 offset:12288
	ds_read_b128 v[10:13], v124 offset:36864
	ds_read_b128 v[18:21], v124 offset:4096
	ds_read_b128 v[2:5], v124 offset:28672
	ds_read_b128 v[98:101], v125 offset:41024
	v_add_f32_dpp v122, v122, v122 quad_perm:[1,0,3,2] row_mask:0xf bank_mask:0xf bound_ctrl:1
	v_pk_mul_f32 v[120:121], v[94:95], v[36:37] op_sel:[1,0]
	v_add_f32_dpp v222, v222, v222 row_mirror row_mask:0xf bank_mask:0xf bound_ctrl:1
	v_add_f32_dpp v122, v122, v122 quad_perm:[2,3,0,1] row_mask:0xf bank_mask:0xf bound_ctrl:1
	v_pk_fma_f32 v[166:167], v[166:167], v[26:27], v[118:119]
	v_add_f32_dpp v222, v230, v230 row_mirror row_mask:0xf bank_mask:0xc bound_ctrl:1
	v_add_f32_dpp v122, v122, v122 row_half_mirror row_mask:0xf bank_mask:0xf bound_ctrl:1
	v_pk_fma_f32 v[164:165], v[164:165], v[28:29], v[120:121]
	s_nop 0
	v_add_f32_dpp v122, v122, v122 row_mirror row_mask:0xf bank_mask:0xf bound_ctrl:1
	s_nop 0
	v_pk_fma_f32 v[166:167], v[30:31], v[122:123], v[166:167] op_sel_hi:[1,0,1]
	v_pk_fma_f32 v[164:165], v[32:33], v[122:123], v[164:165] op_sel_hi:[1,0,1]
	s_waitcnt lgkmcnt(11)
	v_pk_mul_f32 v[114:115], v[166:167], v[42:43]
	v_pk_mul_f32 v[116:117], v[166:167], v[38:39]
	v_pk_fma_f32 v[114:115], v[164:165], v[44:45], v[114:115]
	v_pk_fma_f32 v[116:117], v[164:165], v[40:41], v[116:117]
	v_add_f32_e32 v122, v114, v115
	v_pk_mul_f32 v[118:119], v[96:97], v[54:55] op_sel_hi:[0,1]
	v_add_f32_e32 v231, v116, v117
	ds_read_b128 v[34:37], v124 offset:20736
	ds_read_b128 v[26:29], v124 offset:12544
	ds_read_b128 v[30:33], v124 offset:37120
	ds_read_b128 v[38:41], v124 offset:4352
	ds_read_b128 v[22:25], v124 offset:28928
	v_add_f32_dpp v122, v122, v122 quad_perm:[1,0,3,2] row_mask:0xf bank_mask:0xf bound_ctrl:1
	v_pk_mul_f32 v[120:121], v[96:97], v[56:57] op_sel_hi:[0,1]
	v_add_f32_dpp v223, v223, v223 row_mirror row_mask:0xf bank_mask:0xf bound_ctrl:1
	v_add_f32_dpp v122, v122, v122 quad_perm:[2,3,0,1] row_mask:0xf bank_mask:0xf bound_ctrl:1
	v_pk_fma_f32 v[166:167], v[166:167], v[46:47], v[118:119]
	v_add_f32_dpp v223, v231, v231 row_mirror row_mask:0xf bank_mask:0xc bound_ctrl:1
	v_add_f32_dpp v122, v122, v122 row_half_mirror row_mask:0xf bank_mask:0xf bound_ctrl:1
	v_pk_fma_f32 v[164:165], v[164:165], v[48:49], v[120:121]
	s_nop 0
	v_add_f32_dpp v122, v122, v122 row_mirror row_mask:0xf bank_mask:0xf bound_ctrl:1
	s_nop 0
	v_pk_fma_f32 v[166:167], v[50:51], v[122:123], v[166:167] op_sel_hi:[1,0,1]
	v_pk_fma_f32 v[164:165], v[52:53], v[122:123], v[164:165] op_sel_hi:[1,0,1]
	s_waitcnt lgkmcnt(11)
	v_pk_mul_f32 v[114:115], v[166:167], v[62:63]
	v_pk_mul_f32 v[116:117], v[166:167], v[58:59]
	v_pk_fma_f32 v[114:115], v[164:165], v[64:65], v[114:115]
	v_pk_fma_f32 v[116:117], v[164:165], v[60:61], v[116:117]
	v_add_f32_e32 v122, v114, v115
	v_pk_mul_f32 v[118:119], v[96:97], v[74:75] op_sel:[1,0]
	v_add_f32_e32 v232, v116, v117
	ds_read_b128 v[54:57], v124 offset:20992
	ds_read_b128 v[46:49], v124 offset:12800
	ds_read_b128 v[50:53], v124 offset:37376
	ds_read_b128 v[58:61], v124 offset:4608
	ds_read_b128 v[42:45], v124 offset:29184
	v_add_f32_dpp v122, v122, v122 quad_perm:[1,0,3,2] row_mask:0xf bank_mask:0xf bound_ctrl:1
	v_pk_mul_f32 v[120:121], v[96:97], v[76:77] op_sel:[1,0]
	v_add_f32_dpp v224, v224, v224 row_mirror row_mask:0xf bank_mask:0xf bound_ctrl:1
	v_add_f32_dpp v122, v122, v122 quad_perm:[2,3,0,1] row_mask:0xf bank_mask:0xf bound_ctrl:1
	v_pk_fma_f32 v[166:167], v[166:167], v[66:67], v[118:119]
	v_add_f32_dpp v224, v232, v232 row_mirror row_mask:0xf bank_mask:0xc bound_ctrl:1
	v_add_f32_dpp v122, v122, v122 row_half_mirror row_mask:0xf bank_mask:0xf bound_ctrl:1
	v_pk_fma_f32 v[164:165], v[164:165], v[68:69], v[120:121]
	s_nop 0
	v_add_f32_dpp v122, v122, v122 row_mirror row_mask:0xf bank_mask:0xf bound_ctrl:1
	s_nop 0
	v_pk_fma_f32 v[166:167], v[70:71], v[122:123], v[166:167] op_sel_hi:[1,0,1]
	v_pk_fma_f32 v[164:165], v[72:73], v[122:123], v[164:165] op_sel_hi:[1,0,1]
	s_waitcnt lgkmcnt(11)
; #define LAS __attribute__((address_space(3)))
; template <int CTRL> __device__ __forceinline__ float dpp_f(float x) { return __int_as_float(__builtin_amdgcn_update_dpp(0, __float_as_int(x), CTRL, 0xf, 0xf, false)); }
; __device__ __forceinline__ void phase_scan(const Params& p, LAS unsigned char* lds) {
;     ...
;                         for (int u16 = 0; u16 < 16; ++u16) {
;                             const int s = 16 * hb + u16;
;                             const int sn = (s + 1) & 31;
;                             const f32x4 a_n = *(const LAS f32x4*)(sA + sn * 64), w_n = *(const LAS f32x4*)(sW + sn * 64), b_n = *(const LAS f32x4*)(sB + sn * 64);
;                             const f32x4 k_n = *(const LAS f32x4*)(sK + sn * 64), r_n = *(const LAS f32x4*)(sR + sn * 64);
;                             const float v = vq[u16 >> 2][u16 & 3];
;                             const f32x2 vv = {v, v};
;                             f32x2 pp = S01 * (f32x2){a_[0], a_[1]}; pp = S23 * (f32x2){a_[2], a_[3]} + pp;
;                             f32x2 yy = S01 * (f32x2){rp[0], rp[1]}; yy = S23 * (f32x2){rp[2], rp[3]} + yy;
;                             float sa = pp[0] + pp[1], y = yy[0] + yy[1];
;                             sa += dpp_f<0xB1>(sa); y += dpp_f<0xB1>(y);
;                             sa += dpp_f<0x4E>(sa); y += dpp_f<0x4E>(y);
;                             sa += dpp_f<0x141>(sa); y += dpp_f<0x141>(y);
;                             sa += dpp_f<0x140>(sa); y += dpp_f<0x140>(y);
;                             sY[((s - 1) & 31) * 16 + srow] = y;
;                             const f32x2 sv = {sa, sa};
;                             S01 = S01 * (f32x2){w_[0], w_[1]} + vv * (f32x2){k_[0], k_[1]};
;                             S23 = S23 * (f32x2){w_[2], w_[3]} + vv * (f32x2){k_[2], k_[3]};
;                             S01 = sv * (f32x2){b_[0], b_[1]} + S01;
;                             S23 = sv * (f32x2){b_[2], b_[3]} + S23;
;                             rp = r_;
;                             a_ = a_n; w_ = w_n; b_ = b_n; k_ = k_n; r_ = r_n;
;                         }
	v_pk_mul_f32 v[114:115], v[166:167], v[2:3]
	v_pk_mul_f32 v[116:117], v[166:167], v[78:79]
	v_pk_fma_f32 v[114:115], v[164:165], v[4:5], v[114:115]
	v_pk_fma_f32 v[116:117], v[164:165], v[80:81], v[116:117]
	v_add_f32_e32 v122, v114, v115
	s_waitcnt lgkmcnt(10)
	v_pk_mul_f32 v[118:119], v[98:99], v[14:15] op_sel_hi:[0,1]
	v_add_f32_e32 v233, v116, v117
	ds_read_b128 v[74:77], v124 offset:21248
	ds_read_b128 v[66:69], v124 offset:13056
	ds_read_b128 v[70:73], v124 offset:37632
	ds_read_b128 v[78:81], v124 offset:4864
	ds_read_b128 v[62:65], v124 offset:29440
	v_add_f32_dpp v122, v122, v122 quad_perm:[1,0,3,2] row_mask:0xf bank_mask:0xf bound_ctrl:1
	v_pk_mul_f32 v[120:121], v[98:99], v[16:17] op_sel_hi:[0,1]
	v_add_f32_dpp v225, v225, v225 row_mirror row_mask:0xf bank_mask:0xf bound_ctrl:1
	v_add_f32_dpp v122, v122, v122 quad_perm:[2,3,0,1] row_mask:0xf bank_mask:0xf bound_ctrl:1
	v_pk_fma_f32 v[166:167], v[166:167], v[6:7], v[118:119]
	v_add_f32_dpp v225, v233, v233 row_mirror row_mask:0xf bank_mask:0xc bound_ctrl:1
	v_add_f32_dpp v122, v122, v122 row_half_mirror row_mask:0xf bank_mask:0xf bound_ctrl:1
	v_pk_fma_f32 v[164:165], v[164:165], v[8:9], v[120:121]
	s_nop 0
	v_add_f32_dpp v122, v122, v122 row_mirror row_mask:0xf bank_mask:0xf bound_ctrl:1
	s_nop 0
	v_pk_fma_f32 v[166:167], v[10:11], v[122:123], v[166:167] op_sel_hi:[1,0,1]
	v_pk_fma_f32 v[164:165], v[12:13], v[122:123], v[164:165] op_sel_hi:[1,0,1]
	s_waitcnt lgkmcnt(10)
	v_pk_mul_f32 v[114:115], v[166:167], v[22:23]
	v_pk_mul_f32 v[116:117], v[166:167], v[18:19]
	v_pk_fma_f32 v[114:115], v[164:165], v[24:25], v[114:115]
	v_pk_fma_f32 v[116:117], v[164:165], v[20:21], v[116:117]
	v_add_f32_e32 v122, v114, v115
	v_pk_mul_f32 v[118:119], v[98:99], v[34:35] op_sel:[1,0]
	v_add_f32_e32 v234, v116, v117
	ds_read_b128 v[14:17], v124 offset:21504
	ds_read_b128 v[6:9], v124 offset:13312
	ds_read_b128 v[10:13], v124 offset:37888
	ds_read_b128 v[18:21], v124 offset:5120
	ds_read_b128 v[2:5], v124 offset:29696
	ds_read_b128 v[102:105], v125 offset:41040
	v_add_f32_dpp v122, v122, v122 quad_perm:[1,0,3,2] row_mask:0xf bank_mask:0xf bound_ctrl:1
	v_pk_mul_f32 v[120:121], v[98:99], v[36:37] op_sel:[1,0]
	v_add_f32_dpp v226, v226, v226 row_mirror row_mask:0xf bank_mask:0xf bound_ctrl:1
	v_add_f32_dpp v122, v122, v122 quad_perm:[2,3,0,1] row_mask:0xf bank_mask:0xf bound_ctrl:1
	v_pk_fma_f32 v[166:167], v[166:167], v[26:27], v[118:119]
	v_add_f32_dpp v226, v234, v234 row_mirror row_mask:0xf bank_mask:0xc bound_ctrl:1
	v_add_f32_dpp v122, v122, v122 row_half_mirror row_mask:0xf bank_mask:0xf bound_ctrl:1
	v_pk_fma_f32 v[164:165], v[164:165], v[28:29], v[120:121]
	s_nop 0
	v_add_f32_dpp v122, v122, v122 row_mirror row_mask:0xf bank_mask:0xf bound_ctrl:1
	s_nop 0
	v_pk_fma_f32 v[166:167], v[30:31], v[122:123], v[166:167] op_sel_hi:[1,0,1]
	v_pk_fma_f32 v[164:165], v[32:33], v[122:123], v[164:165] op_sel_hi:[1,0,1]
	s_waitcnt lgkmcnt(11)
	v_pk_mul_f32 v[114:115], v[166:167], v[42:43]
	v_pk_mul_f32 v[116:117], v[166:167], v[38:39]
	v_pk_fma_f32 v[114:115], v[164:165], v[44:45], v[114:115]
	v_pk_fma_f32 v[116:117], v[164:165], v[40:41], v[116:117]
	v_add_f32_e32 v122, v114, v115
	v_pk_mul_f32 v[118:119], v[100:101], v[54:55] op_sel_hi:[0,1]
	v_add_f32_e32 v235, v116, v117
	ds_read_b128 v[34:37], v124 offset:21760
	ds_read_b128 v[26:29], v124 offset:13568
	ds_read_b128 v[30:33], v124 offset:38144
	ds_read_b128 v[38:41], v124 offset:5376
	ds_read_b128 v[22:25], v124 offset:29952
	v_add_f32_dpp v122, v122, v122 quad_perm:[1,0,3,2] row_mask:0xf bank_mask:0xf bound_ctrl:1
	v_pk_mul_f32 v[120:121], v[100:101], v[56:57] op_sel_hi:[0,1]
	v_add_f32_dpp v227, v227, v227 row_mirror row_mask:0xf bank_mask:0xf bound_ctrl:1
	v_add_f32_dpp v122, v122, v122 quad_perm:[2,3,0,1] row_mask:0xf bank_mask:0xf bound_ctrl:1
	v_pk_fma_f32 v[166:167], v[166:167], v[46:47], v[118:119]
	v_add_f32_dpp v227, v235, v235 row_mirror row_mask:0xf bank_mask:0xc bound_ctrl:1
	v_add_f32_dpp v122, v122, v122 row_half_mirror row_mask:0xf bank_mask:0xf bound_ctrl:1
	v_pk_fma_f32 v[164:165], v[164:165], v[48:49], v[120:121]
	v_add_f32_dpp v220, v220, v220 row_half_mirror row_mask:0xf bank_mask:0xf bound_ctrl:1
	v_add_f32_dpp v122, v122, v122 row_mirror row_mask:0xf bank_mask:0xf bound_ctrl:1
	v_add_f32_dpp v221, v221, v221 row_half_mirror row_mask:0xf bank_mask:0xf bound_ctrl:1
	v_add_f32_dpp v222, v222, v222 row_half_mirror row_mask:0xf bank_mask:0xf bound_ctrl:1
	v_pk_fma_f32 v[166:167], v[50:51], v[122:123], v[166:167] op_sel_hi:[1,0,1]
	v_pk_fma_f32 v[164:165], v[52:53], v[122:123], v[164:165] op_sel_hi:[1,0,1]
	v_add_f32_dpp v223, v223, v223 row_half_mirror row_mask:0xf bank_mask:0xf bound_ctrl:1
	v_add_f32_dpp v220, v224, v224 row_half_mirror row_mask:0xf bank_mask:0xa bound_ctrl:1
	s_waitcnt lgkmcnt(11)
; #define LAS __attribute__((address_space(3)))
; template <int CTRL> __device__ __forceinline__ float dpp_f(float x) { return __int_as_float(__builtin_amdgcn_update_dpp(0, __float_as_int(x), CTRL, 0xf, 0xf, false)); }
; __device__ __forceinline__ void phase_scan(const Params& p, LAS unsigned char* lds) {
;     ...
;                         for (int u16 = 0; u16 < 16; ++u16) {
;                             const int s = 16 * hb + u16;
;                             const int sn = (s + 1) & 31;
;                             const f32x4 a_n = *(const LAS f32x4*)(sA + sn * 64), w_n = *(const LAS f32x4*)(sW + sn * 64), b_n = *(const LAS f32x4*)(sB + sn * 64);
;                             const f32x4 k_n = *(const LAS f32x4*)(sK + sn * 64), r_n = *(const LAS f32x4*)(sR + sn * 64);
;                             const float v = vq[u16 >> 2][u16 & 3];
;                             const f32x2 vv = {v, v};
;                             f32x2 pp = S01 * (f32x2){a_[0], a_[1]}; pp = S23 * (f32x2){a_[2], a_[3]} + pp;
;                             f32x2 yy = S01 * (f32x2){rp[0], rp[1]}; yy = S23 * (f32x2){rp[2], rp[3]} + yy;
;                             float sa = pp[0] + pp[1], y = yy[0] + yy[1];
;                             sa += dpp_f<0xB1>(sa); y += dpp_f<0xB1>(y);
;                             sa += dpp_f<0x4E>(sa); y += dpp_f<0x4E>(y);
;                             sa += dpp_f<0x141>(sa); y += dpp_f<0x141>(y);
;                             sa += dpp_f<0x140>(sa); y += dpp_f<0x140>(y);
;                             sY[((s - 1) & 31) * 16 + srow] = y;
;                             const f32x2 sv = {sa, sa};
;                             S01 = S01 * (f32x2){w_[0], w_[1]} + vv * (f32x2){k_[0], k_[1]};
;                             S23 = S23 * (f32x2){w_[2], w_[3]} + vv * (f32x2){k_[2], k_[3]};
;                             S01 = sv * (f32x2){b_[0], b_[1]} + S01;
;                             S23 = sv * (f32x2){b_[2], b_[3]} + S23;
;                             rp = r_;
;                             a_ = a_n; w_ = w_n; b_ = b_n; k_ = k_n; r_ = r_n;
;                         }
	v_pk_mul_f32 v[114:115], v[166:167], v[62:63]
	v_pk_mul_f32 v[116:117], v[166:167], v[58:59]
	v_pk_fma_f32 v[114:115], v[164:165], v[64:65], v[114:115]
	v_pk_fma_f32 v[116:117], v[164:165], v[60:61], v[116:117]
	v_add_f32_e32 v122, v114, v115
	v_pk_mul_f32 v[118:119], v[100:101], v[74:75] op_sel:[1,0]
	v_add_f32_e32 v204, v116, v117
	ds_read_b128 v[54:57], v124 offset:22016
	ds_read_b128 v[46:49], v124 offset:13824
	ds_read_b128 v[50:53], v124 offset:38400
	ds_read_b128 v[58:61], v124 offset:5632
	ds_read_b128 v[42:45], v124 offset:30208
	v_add_f32_dpp v122, v122, v122 quad_perm:[1,0,3,2] row_mask:0xf bank_mask:0xf bound_ctrl:1
	v_pk_mul_f32 v[120:121], v[100:101], v[76:77] op_sel:[1,0]
	v_add_f32_dpp v221, v225, v225 row_half_mirror row_mask:0xf bank_mask:0xa bound_ctrl:1
	v_add_f32_dpp v122, v122, v122 quad_perm:[2,3,0,1] row_mask:0xf bank_mask:0xf bound_ctrl:1
	v_pk_fma_f32 v[166:167], v[166:167], v[66:67], v[118:119]
	v_add_f32_dpp v222, v226, v226 row_half_mirror row_mask:0xf bank_mask:0xa bound_ctrl:1
	v_add_f32_dpp v122, v122, v122 row_half_mirror row_mask:0xf bank_mask:0xf bound_ctrl:1
	v_pk_fma_f32 v[164:165], v[164:165], v[68:69], v[120:121]
	v_add_f32_dpp v223, v227, v227 row_half_mirror row_mask:0xf bank_mask:0xa bound_ctrl:1
	v_add_f32_dpp v122, v122, v122 row_mirror row_mask:0xf bank_mask:0xf bound_ctrl:1
	v_add_f32_dpp v220, v220, v220 quad_perm:[1,0,3,2] row_mask:0xf bank_mask:0xf bound_ctrl:1
	v_add_f32_dpp v221, v221, v221 quad_perm:[1,0,3,2] row_mask:0xf bank_mask:0xf bound_ctrl:1
	v_pk_fma_f32 v[166:167], v[70:71], v[122:123], v[166:167] op_sel_hi:[1,0,1]
	v_pk_fma_f32 v[164:165], v[72:73], v[122:123], v[164:165] op_sel_hi:[1,0,1]
	v_add_f32_dpp v222, v222, v222 quad_perm:[1,0,3,2] row_mask:0xf bank_mask:0xf bound_ctrl:1
	v_add_f32_dpp v223, v223, v223 quad_perm:[1,0,3,2] row_mask:0xf bank_mask:0xf bound_ctrl:1
	s_waitcnt lgkmcnt(11)
	v_pk_mul_f32 v[114:115], v[166:167], v[2:3]
	v_pk_mul_f32 v[116:117], v[166:167], v[78:79]
	v_pk_fma_f32 v[114:115], v[164:165], v[4:5], v[114:115]
	v_pk_fma_f32 v[116:117], v[164:165], v[80:81], v[116:117]
	v_add_f32_e32 v122, v114, v115
	s_waitcnt lgkmcnt(10)
	v_pk_mul_f32 v[118:119], v[102:103], v[14:15] op_sel_hi:[0,1]
	v_add_f32_e32 v205, v116, v117
	ds_read_b128 v[74:77], v124 offset:22272
	ds_read_b128 v[66:69], v124 offset:14080
	ds_read_b128 v[70:73], v124 offset:38656
	ds_read_b128 v[78:81], v124 offset:5888
	ds_read_b128 v[62:65], v124 offset:30464
	v_add_f32_dpp v122, v122, v122 quad_perm:[1,0,3,2] row_mask:0xf bank_mask:0xf bound_ctrl:1
	v_pk_mul_f32 v[120:121], v[102:103], v[16:17] op_sel_hi:[0,1]
	v_add_f32_dpp v220, v220, v220 quad_perm:[2,3,0,1] row_mask:0xf bank_mask:0xf bound_ctrl:1
	v_add_f32_dpp v122, v122, v122 quad_perm:[2,3,0,1] row_mask:0xf bank_mask:0xf bound_ctrl:1
	v_pk_fma_f32 v[166:167], v[166:167], v[6:7], v[118:119]
	v_add_f32_dpp v221, v221, v221 quad_perm:[2,3,0,1] row_mask:0xf bank_mask:0xf bound_ctrl:1
	v_add_f32_dpp v122, v122, v122 row_half_mirror row_mask:0xf bank_mask:0xf bound_ctrl:1
	v_pk_fma_f32 v[164:165], v[164:165], v[8:9], v[120:121]
	v_add_f32_dpp v222, v222, v222 quad_perm:[2,3,0,1] row_mask:0xf bank_mask:0xf bound_ctrl:1
	v_add_f32_dpp v122, v122, v122 row_mirror row_mask:0xf bank_mask:0xf bound_ctrl:1
	v_add_f32_dpp v223, v223, v223 quad_perm:[2,3,0,1] row_mask:0xf bank_mask:0xf bound_ctrl:1
	v_cndmask_b32_e64 v202, v220, v221, s[34:35]
	v_pk_fma_f32 v[166:167], v[10:11], v[122:123], v[166:167] op_sel_hi:[1,0,1]
	v_pk_fma_f32 v[164:165], v[12:13], v[122:123], v[164:165] op_sel_hi:[1,0,1]
	v_cndmask_b32_e64 v202, v202, v222, s[56:57]
	v_cndmask_b32_e64 v202, v202, v223, s[98:99]
	s_waitcnt lgkmcnt(10)
	v_pk_mul_f32 v[114:115], v[166:167], v[22:23]
	v_pk_mul_f32 v[116:117], v[166:167], v[18:19]
	v_pk_fma_f32 v[114:115], v[164:165], v[24:25], v[114:115]
	v_pk_fma_f32 v[116:117], v[164:165], v[20:21], v[116:117]
	v_add_f32_e32 v122, v114, v115
	v_pk_mul_f32 v[118:119], v[102:103], v[34:35] op_sel:[1,0]
	v_add_f32_e32 v206, v116, v117
	ds_read_b128 v[14:17], v124 offset:22528
	ds_read_b128 v[6:9], v124 offset:14336
	ds_read_b128 v[10:13], v124 offset:38912
	ds_read_b128 v[18:21], v124 offset:6144
	ds_read_b128 v[2:5], v124 offset:30720
	ds_read_b128 v[106:109], v125 offset:41056
	v_add_f32_dpp v122, v122, v122 quad_perm:[1,0,3,2] row_mask:0xf bank_mask:0xf bound_ctrl:1
	v_pk_mul_f32 v[120:121], v[102:103], v[36:37] op_sel:[1,0]
	v_cvt_f16_f32_e32 v203, v202
	v_add_f32_dpp v122, v122, v122 quad_perm:[2,3,0,1] row_mask:0xf bank_mask:0xf bound_ctrl:1
	v_pk_fma_f32 v[166:167], v[166:167], v[26:27], v[118:119]
	global_store_short v[126:127], v203, off
	v_add_f32_dpp v122, v122, v122 row_half_mirror row_mask:0xf bank_mask:0xf bound_ctrl:1
	v_pk_fma_f32 v[164:165], v[164:165], v[28:29], v[120:121]
	v_lshl_add_u64 v[126:127], v[126:127], 0, s[100:101]
	v_add_f32_dpp v122, v122, v122 row_mirror row_mask:0xf bank_mask:0xf bound_ctrl:1
	s_nop 0
	v_pk_fma_f32 v[166:167], v[30:31], v[122:123], v[166:167] op_sel_hi:[1,0,1]
	v_pk_fma_f32 v[164:165], v[32:33], v[122:123], v[164:165] op_sel_hi:[1,0,1]
	s_waitcnt lgkmcnt(11)
; #define LAS __attribute__((address_space(3)))
; template <int CTRL> __device__ __forceinline__ float dpp_f(float x) { return __int_as_float(__builtin_amdgcn_update_dpp(0, __float_as_int(x), CTRL, 0xf, 0xf, false)); }
; __device__ __forceinline__ void phase_scan(const Params& p, LAS unsigned char* lds) {
;     ...
;                         for (int u16 = 0; u16 < 16; ++u16) {
;                             const int s = 16 * hb + u16;
;                             const int sn = (s + 1) & 31;
;                             const f32x4 a_n = *(const LAS f32x4*)(sA + sn * 64), w_n = *(const LAS f32x4*)(sW + sn * 64), b_n = *(const LAS f32x4*)(sB + sn * 64);
;                             const f32x4 k_n = *(const LAS f32x4*)(sK + sn * 64), r_n = *(const LAS f32x4*)(sR + sn * 64);
;                             const float v = vq[u16 >> 2][u16 & 3];
;                             const f32x2 vv = {v, v};
;                             f32x2 pp = S01 * (f32x2){a_[0], a_[1]}; pp = S23 * (f32x2){a_[2], a_[3]} + pp;
;                             f32x2 yy = S01 * (f32x2){rp[0], rp[1]}; yy = S23 * (f32x2){rp[2], rp[3]} + yy;
;                             float sa = pp[0] + pp[1], y = yy[0] + yy[1];
;                             sa += dpp_f<0xB1>(sa); y += dpp_f<0xB1>(y);
;                             sa += dpp_f<0x4E>(sa); y += dpp_f<0x4E>(y);
;                             sa += dpp_f<0x141>(sa); y += dpp_f<0x141>(y);
;                             sa += dpp_f<0x140>(sa); y += dpp_f<0x140>(y);
;                             sY[((s - 1) & 31) * 16 + srow] = y;
;                             const f32x2 sv = {sa, sa};
;                             S01 = S01 * (f32x2){w_[0], w_[1]} + vv * (f32x2){k_[0], k_[1]};
;                             S23 = S23 * (f32x2){w_[2], w_[3]} + vv * (f32x2){k_[2], k_[3]};
;                             S01 = sv * (f32x2){b_[0], b_[1]} + S01;
;                             S23 = sv * (f32x2){b_[2], b_[3]} + S23;
;                             rp = r_;
;                             a_ = a_n; w_ = w_n; b_ = b_n; k_ = k_n; r_ = r_n;
;                         }
	v_pk_mul_f32 v[114:115], v[166:167], v[42:43]
	v_pk_mul_f32 v[116:117], v[166:167], v[38:39]
	v_pk_fma_f32 v[114:115], v[164:165], v[44:45], v[114:115]
	v_pk_fma_f32 v[116:117], v[164:165], v[40:41], v[116:117]
	v_add_f32_e32 v122, v114, v115
	v_pk_mul_f32 v[118:119], v[104:105], v[54:55] op_sel_hi:[0,1]
	v_add_f32_e32 v207, v116, v117
	ds_read_b128 v[34:37], v124 offset:22784
	ds_read_b128 v[26:29], v124 offset:14592
	ds_read_b128 v[30:33], v124 offset:39168
	ds_read_b128 v[38:41], v124 offset:6400
	ds_read_b128 v[22:25], v124 offset:30976
	v_add_f32_dpp v122, v122, v122 quad_perm:[1,0,3,2] row_mask:0xf bank_mask:0xf bound_ctrl:1
	v_pk_mul_f32 v[120:121], v[104:105], v[56:57] op_sel_hi:[0,1]
	s_nop 0
	v_add_f32_dpp v122, v122, v122 quad_perm:[2,3,0,1] row_mask:0xf bank_mask:0xf bound_ctrl:1
	v_pk_fma_f32 v[166:167], v[166:167], v[46:47], v[118:119]
	s_nop 0
	v_add_f32_dpp v122, v122, v122 row_half_mirror row_mask:0xf bank_mask:0xf bound_ctrl:1
	v_pk_fma_f32 v[164:165], v[164:165], v[48:49], v[120:121]
	s_nop 0
	v_add_f32_dpp v122, v122, v122 row_mirror row_mask:0xf bank_mask:0xf bound_ctrl:1
	s_nop 0
	v_pk_fma_f32 v[166:167], v[50:51], v[122:123], v[166:167] op_sel_hi:[1,0,1]
	v_pk_fma_f32 v[164:165], v[52:53], v[122:123], v[164:165] op_sel_hi:[1,0,1]
	s_waitcnt lgkmcnt(11)
	v_pk_mul_f32 v[114:115], v[166:167], v[62:63]
	v_pk_mul_f32 v[116:117], v[166:167], v[58:59]
	v_pk_fma_f32 v[114:115], v[164:165], v[64:65], v[114:115]
	v_pk_fma_f32 v[116:117], v[164:165], v[60:61], v[116:117]
	v_add_f32_e32 v122, v114, v115
	v_pk_mul_f32 v[118:119], v[104:105], v[74:75] op_sel:[1,0]
	v_add_f32_e32 v208, v116, v117
	ds_read_b128 v[54:57], v124 offset:23040
	ds_read_b128 v[46:49], v124 offset:14848
	ds_read_b128 v[50:53], v124 offset:39424
	ds_read_b128 v[58:61], v124 offset:6656
	ds_read_b128 v[42:45], v124 offset:31232
	v_add_f32_dpp v122, v122, v122 quad_perm:[1,0,3,2] row_mask:0xf bank_mask:0xf bound_ctrl:1
	v_pk_mul_f32 v[120:121], v[104:105], v[76:77] op_sel:[1,0]
	s_nop 0
	v_add_f32_dpp v122, v122, v122 quad_perm:[2,3,0,1] row_mask:0xf bank_mask:0xf bound_ctrl:1
	v_pk_fma_f32 v[166:167], v[166:167], v[66:67], v[118:119]
	s_nop 0
	v_add_f32_dpp v122, v122, v122 row_half_mirror row_mask:0xf bank_mask:0xf bound_ctrl:1
	v_pk_fma_f32 v[164:165], v[164:165], v[68:69], v[120:121]
	s_nop 0
	v_add_f32_dpp v122, v122, v122 row_mirror row_mask:0xf bank_mask:0xf bound_ctrl:1
	s_nop 0
	v_pk_fma_f32 v[166:167], v[70:71], v[122:123], v[166:167] op_sel_hi:[1,0,1]
	v_pk_fma_f32 v[164:165], v[72:73], v[122:123], v[164:165] op_sel_hi:[1,0,1]
	s_waitcnt lgkmcnt(11)
	v_pk_mul_f32 v[114:115], v[166:167], v[2:3]
	v_pk_mul_f32 v[116:117], v[166:167], v[78:79]
	v_pk_fma_f32 v[114:115], v[164:165], v[4:5], v[114:115]
	v_pk_fma_f32 v[116:117], v[164:165], v[80:81], v[116:117]
	v_add_f32_e32 v122, v114, v115
	s_waitcnt lgkmcnt(10)
	v_pk_mul_f32 v[118:119], v[106:107], v[14:15] op_sel_hi:[0,1]
	v_add_f32_e32 v209, v116, v117
	ds_read_b128 v[74:77], v124 offset:23296
	ds_read_b128 v[66:69], v124 offset:15104
	ds_read_b128 v[70:73], v124 offset:39680
	ds_read_b128 v[78:81], v124 offset:6912
	ds_read_b128 v[62:65], v124 offset:31488
	v_add_f32_dpp v122, v122, v122 quad_perm:[1,0,3,2] row_mask:0xf bank_mask:0xf bound_ctrl:1
	v_pk_mul_f32 v[120:121], v[106:107], v[16:17] op_sel_hi:[0,1]
	s_nop 0
	v_add_f32_dpp v122, v122, v122 quad_perm:[2,3,0,1] row_mask:0xf bank_mask:0xf bound_ctrl:1
	v_pk_fma_f32 v[166:167], v[166:167], v[6:7], v[118:119]
	s_nop 0
	v_add_f32_dpp v122, v122, v122 row_half_mirror row_mask:0xf bank_mask:0xf bound_ctrl:1
	v_pk_fma_f32 v[164:165], v[164:165], v[8:9], v[120:121]
	s_nop 0
	v_add_f32_dpp v122, v122, v122 row_mirror row_mask:0xf bank_mask:0xf bound_ctrl:1
	s_nop 0
	v_pk_fma_f32 v[166:167], v[10:11], v[122:123], v[166:167] op_sel_hi:[1,0,1]
	v_pk_fma_f32 v[164:165], v[12:13], v[122:123], v[164:165] op_sel_hi:[1,0,1]
	s_waitcnt lgkmcnt(10)
	v_pk_mul_f32 v[114:115], v[166:167], v[22:23]
	v_pk_mul_f32 v[116:117], v[166:167], v[18:19]
	v_pk_fma_f32 v[114:115], v[164:165], v[24:25], v[114:115]
	v_pk_fma_f32 v[116:117], v[164:165], v[20:21], v[116:117]
	v_add_f32_e32 v122, v114, v115
	v_pk_mul_f32 v[118:119], v[106:107], v[34:35] op_sel:[1,0]
	v_add_f32_e32 v210, v116, v117
	ds_read_b128 v[14:17], v124 offset:23552
	ds_read_b128 v[6:9], v124 offset:15360
	ds_read_b128 v[10:13], v124 offset:39936
	ds_read_b128 v[18:21], v124 offset:7168
	ds_read_b128 v[2:5], v124 offset:31744
	ds_read_b128 v[110:113], v125 offset:41072
	v_add_f32_dpp v122, v122, v122 quad_perm:[1,0,3,2] row_mask:0xf bank_mask:0xf bound_ctrl:1
	v_pk_mul_f32 v[120:121], v[106:107], v[36:37] op_sel:[1,0]
	s_nop 0
	v_add_f32_dpp v122, v122, v122 quad_perm:[2,3,0,1] row_mask:0xf bank_mask:0xf bound_ctrl:1
	v_pk_fma_f32 v[166:167], v[166:167], v[26:27], v[118:119]
	s_nop 0
	v_add_f32_dpp v122, v122, v122 row_half_mirror row_mask:0xf bank_mask:0xf bound_ctrl:1
	v_pk_fma_f32 v[164:165], v[164:165], v[28:29], v[120:121]
	s_nop 0
	v_add_f32_dpp v122, v122, v122 row_mirror row_mask:0xf bank_mask:0xf bound_ctrl:1
	s_nop 0
	v_pk_fma_f32 v[166:167], v[30:31], v[122:123], v[166:167] op_sel_hi:[1,0,1]
	v_pk_fma_f32 v[164:165], v[32:33], v[122:123], v[164:165] op_sel_hi:[1,0,1]
	s_waitcnt lgkmcnt(11)
; #define LAS __attribute__((address_space(3)))
; template <int CTRL> __device__ __forceinline__ float dpp_f(float x) { return __int_as_float(__builtin_amdgcn_update_dpp(0, __float_as_int(x), CTRL, 0xf, 0xf, false)); }
; #define LDS_BAR() do { asm volatile("s_waitcnt lgkmcnt(0)" ::: "memory"); __builtin_amdgcn_s_barrier(); asm volatile("" ::: "memory"); } while (0)
; __device__ __forceinline__ void phase_scan(const Params& p, LAS unsigned char* lds) {
;     ...
;                         for (int u16 = 0; u16 < 16; ++u16) {
;                             const int s = 16 * hb + u16;
;                             const int sn = (s + 1) & 31;
;                             const f32x4 a_n = *(const LAS f32x4*)(sA + sn * 64), w_n = *(const LAS f32x4*)(sW + sn * 64), b_n = *(const LAS f32x4*)(sB + sn * 64);
;                             const f32x4 k_n = *(const LAS f32x4*)(sK + sn * 64), r_n = *(const LAS f32x4*)(sR + sn * 64);
;                             const float v = vq[u16 >> 2][u16 & 3];
;                             const f32x2 vv = {v, v};
;                             f32x2 pp = S01 * (f32x2){a_[0], a_[1]}; pp = S23 * (f32x2){a_[2], a_[3]} + pp;
;                             f32x2 yy = S01 * (f32x2){rp[0], rp[1]}; yy = S23 * (f32x2){rp[2], rp[3]} + yy;
;                             float sa = pp[0] + pp[1], y = yy[0] + yy[1];
;                             sa += dpp_f<0xB1>(sa); y += dpp_f<0xB1>(y);
;                             sa += dpp_f<0x4E>(sa); y += dpp_f<0x4E>(y);
;                             sa += dpp_f<0x141>(sa); y += dpp_f<0x141>(y);
;                             sa += dpp_f<0x140>(sa); y += dpp_f<0x140>(y);
;                             sY[((s - 1) & 31) * 16 + srow] = y;
;                             const f32x2 sv = {sa, sa};
;                             S01 = S01 * (f32x2){w_[0], w_[1]} + vv * (f32x2){k_[0], k_[1]};
;                             S23 = S23 * (f32x2){w_[2], w_[3]} + vv * (f32x2){k_[2], k_[3]};
;                             S01 = sv * (f32x2){b_[0], b_[1]} + S01;
;                             S23 = sv * (f32x2){b_[2], b_[3]} + S23;
;                             rp = r_;
;                             a_ = a_n; w_ = w_n; b_ = b_n; k_ = k_n; r_ = r_n;
;                         }
;     ...
;             LDS_BAR();
	v_pk_mul_f32 v[114:115], v[166:167], v[42:43]
	v_pk_mul_f32 v[116:117], v[166:167], v[38:39]
	v_pk_fma_f32 v[114:115], v[164:165], v[44:45], v[114:115]
	v_pk_fma_f32 v[116:117], v[164:165], v[40:41], v[116:117]
	v_add_f32_e32 v122, v114, v115
	v_pk_mul_f32 v[118:119], v[108:109], v[54:55] op_sel_hi:[0,1]
	v_add_f32_e32 v211, v116, v117
	ds_read_b128 v[34:37], v124 offset:23808
	ds_read_b128 v[26:29], v124 offset:15616
	ds_read_b128 v[30:33], v124 offset:40192
	ds_read_b128 v[38:41], v124 offset:7424
	ds_read_b128 v[22:25], v124 offset:32000
	v_add_f32_dpp v122, v122, v122 quad_perm:[1,0,3,2] row_mask:0xf bank_mask:0xf bound_ctrl:1
	v_pk_mul_f32 v[120:121], v[108:109], v[56:57] op_sel_hi:[0,1]
	s_nop 0
	v_add_f32_dpp v122, v122, v122 quad_perm:[2,3,0,1] row_mask:0xf bank_mask:0xf bound_ctrl:1
	v_pk_fma_f32 v[166:167], v[166:167], v[46:47], v[118:119]
	s_nop 0
	v_add_f32_dpp v122, v122, v122 row_half_mirror row_mask:0xf bank_mask:0xf bound_ctrl:1
	v_pk_fma_f32 v[164:165], v[164:165], v[48:49], v[120:121]
	s_nop 0
	v_add_f32_dpp v122, v122, v122 row_mirror row_mask:0xf bank_mask:0xf bound_ctrl:1
	s_nop 0
	v_pk_fma_f32 v[166:167], v[50:51], v[122:123], v[166:167] op_sel_hi:[1,0,1]
	v_pk_fma_f32 v[164:165], v[52:53], v[122:123], v[164:165] op_sel_hi:[1,0,1]
	s_waitcnt lgkmcnt(11)
	v_pk_mul_f32 v[114:115], v[166:167], v[62:63]
	v_pk_mul_f32 v[116:117], v[166:167], v[58:59]
	v_pk_fma_f32 v[114:115], v[164:165], v[64:65], v[114:115]
	v_pk_fma_f32 v[116:117], v[164:165], v[60:61], v[116:117]
	v_add_f32_e32 v122, v114, v115
	v_pk_mul_f32 v[118:119], v[108:109], v[74:75] op_sel:[1,0]
	v_add_f32_e32 v212, v116, v117
	ds_read_b128 v[54:57], v124 offset:24064
	ds_read_b128 v[46:49], v124 offset:15872
	ds_read_b128 v[50:53], v124 offset:40448
	ds_read_b128 v[58:61], v124 offset:7680
	ds_read_b128 v[42:45], v124 offset:32256
	v_add_f32_dpp v122, v122, v122 quad_perm:[1,0,3,2] row_mask:0xf bank_mask:0xf bound_ctrl:1
	v_pk_mul_f32 v[120:121], v[108:109], v[76:77] op_sel:[1,0]
	s_nop 0
	v_add_f32_dpp v122, v122, v122 quad_perm:[2,3,0,1] row_mask:0xf bank_mask:0xf bound_ctrl:1
	v_pk_fma_f32 v[166:167], v[166:167], v[66:67], v[118:119]
	s_nop 0
	v_add_f32_dpp v122, v122, v122 row_half_mirror row_mask:0xf bank_mask:0xf bound_ctrl:1
	v_pk_fma_f32 v[164:165], v[164:165], v[68:69], v[120:121]
	s_nop 0
	v_add_f32_dpp v122, v122, v122 row_mirror row_mask:0xf bank_mask:0xf bound_ctrl:1
	s_nop 0
	v_pk_fma_f32 v[166:167], v[70:71], v[122:123], v[166:167] op_sel_hi:[1,0,1]
	v_pk_fma_f32 v[164:165], v[72:73], v[122:123], v[164:165] op_sel_hi:[1,0,1]
	s_waitcnt lgkmcnt(11)
	v_pk_mul_f32 v[114:115], v[166:167], v[2:3]
	v_pk_mul_f32 v[116:117], v[166:167], v[78:79]
	v_pk_fma_f32 v[114:115], v[164:165], v[4:5], v[114:115]
	v_pk_fma_f32 v[116:117], v[164:165], v[80:81], v[116:117]
	v_add_f32_e32 v122, v114, v115
	s_waitcnt lgkmcnt(10)
	v_pk_mul_f32 v[118:119], v[110:111], v[14:15] op_sel_hi:[0,1]
	v_add_f32_e32 v213, v116, v117
	ds_read_b128 v[74:77], v124 offset:24320
	ds_read_b128 v[66:69], v124 offset:16128
	ds_read_b128 v[70:73], v124 offset:40704
	ds_read_b128 v[78:81], v124 offset:7936
	ds_read_b128 v[62:65], v124 offset:32512
	v_add_f32_dpp v122, v122, v122 quad_perm:[1,0,3,2] row_mask:0xf bank_mask:0xf bound_ctrl:1
	v_pk_mul_f32 v[120:121], v[110:111], v[16:17] op_sel_hi:[0,1]
	s_nop 0
	v_add_f32_dpp v122, v122, v122 quad_perm:[2,3,0,1] row_mask:0xf bank_mask:0xf bound_ctrl:1
	v_pk_fma_f32 v[166:167], v[166:167], v[6:7], v[118:119]
	s_nop 0
	v_add_f32_dpp v122, v122, v122 row_half_mirror row_mask:0xf bank_mask:0xf bound_ctrl:1
	v_pk_fma_f32 v[164:165], v[164:165], v[8:9], v[120:121]
	s_nop 0
	v_add_f32_dpp v122, v122, v122 row_mirror row_mask:0xf bank_mask:0xf bound_ctrl:1
	s_nop 0
	v_pk_fma_f32 v[166:167], v[10:11], v[122:123], v[166:167] op_sel_hi:[1,0,1]
	v_pk_fma_f32 v[164:165], v[12:13], v[122:123], v[164:165] op_sel_hi:[1,0,1]
	s_waitcnt lgkmcnt(0)
	s_barrier
	s_add_i32 s81, s81, 1
	s_addk_i32 s82, 0x200
	s_cmpk_eq_i32 s81, 0x100
	s_cbranch_scc0 .Lscan_trip
	s_branch .LBB0_620
